# grid barrier: all waiters poll the top arrival counter for >= (gen+1)*nx; TOPGEN and XGEN hops removed
# speedup vs baseline: 1.0111x; 1.0004x over previous
; __device__ __forceinline__ unsigned xb_ld(unsigned* p)              { return __hip_atomic_load(p, __ATOMIC_RELAXED, __HIP_MEMORY_SCOPE_AGENT); }
; __device__ __forceinline__ unsigned xb_add(unsigned* p, unsigned v) { return __hip_atomic_fetch_add(p, v, __ATOMIC_RELAXED, __HIP_MEMORY_SCOPE_AGENT); }
; #define XB_SPIN(cond, bar) do { unsigned _sp = 0; while (cond) { __builtin_amdgcn_s_sleep(1); \
;     if ((++_sp & 255u) == 0u) { if (xb_ld(&(bar)[XB_TMO])) break; if (_sp > XB_SPIN_CAP) { atomicAdd(&(bar)[XB_TMO], 1u); break; } } } } while (0)
; __device__ __forceinline__ void xcd_barrier(unsigned* bar, volatile LAS unsigned* st) {
;     ...
;     const unsigned old = xb_add(&bar[XB_XSUB(x)], 1u);
;     const unsigned gen = old / nloc;
;     if (old + 1u == (gen + 1u) * nloc) {
;       __builtin_amdgcn_fence(__ATOMIC_RELEASE, "agent");
;       asm volatile("s_waitcnt vmcnt(0)" ::: "memory");
;       const unsigned og = xb_add(&bar[XB_TOP], 1u);
;       const unsigned tg = og / nx;
;       if (og + 1u == (tg + 1u) * nx) xb_add(&bar[XB_TOPGEN], 1u);
;       else XB_SPIN(xb_ld(&bar[XB_TOPGEN]) == tg, bar);
;       __builtin_amdgcn_fence(__ATOMIC_ACQUIRE, "agent");
;       xb_add(&bar[XB_XGEN(x)], 1u);
;       asm volatile("s_waitcnt vmcnt(0)" ::: "memory");
;     } else {
;       XB_SPIN(xb_ld(&bar[XB_XGEN(x)]) == gen, bar);
.LBB0_175:
	v_mov_b32_e32 v246, v0
	s_mov_b64 s[0:1], exec
	s_lshl_b32 s2, s18, 8
	v_mbcnt_lo_u32_b32 v1, s0, 0
	s_add_u32 s10, s8, s2
	v_mbcnt_hi_u32_b32 v1, s1, v1
	s_addc_u32 s11, s9, 0
	v_cmp_eq_u32_e32 vcc, 0, v1
	s_and_saveexec_b64 s[2:3], vcc
	s_cbranch_execz .LBB0_177
	s_bcnt1_i32_b64 s0, s[0:1]
	v_mov_b32_e32 v3, 0x1000
	v_mov_b32_e32 v4, s0
	global_atomic_add v3, v3, v4, s[10:11] offset:1024 sc0
.LBB0_177:
	s_or_b64 exec, exec, s[2:3]
	v_cvt_f32_u32_e32 v4, v2
	s_waitcnt vmcnt(0)
	v_readfirstlane_b32 s0, v3
	v_sub_u32_e32 v3, 0, v2
	v_rcp_iflag_f32_e32 v4, v4
	v_add_u32_e32 v5, s0, v1
	v_mul_f32_e32 v4, 0x4f7ffffe, v4
	v_cvt_u32_f32_e32 v4, v4
	v_mul_lo_u32 v1, v3, v4
	v_mul_hi_u32 v1, v4, v1
	v_add_u32_e32 v1, v4, v1
	v_mul_hi_u32 v1, v5, v1
	v_mul_lo_u32 v3, v1, v2
	v_sub_u32_e32 v3, v5, v3
	v_add_u32_e32 v4, 1, v1
	v_cmp_ge_u32_e32 vcc, v3, v2
	s_nop 1
	v_cndmask_b32_e32 v1, v1, v4, vcc
	v_sub_u32_e32 v4, v3, v2
	v_cndmask_b32_e32 v3, v3, v4, vcc
	v_add_u32_e32 v4, 1, v1
	v_cmp_ge_u32_e32 vcc, v3, v2
	v_add_u32_e32 v3, 1, v5
	s_nop 0
	v_cndmask_b32_e32 v1, v1, v4, vcc
	v_mul_lo_u32 v4, v2, v1
	v_add_u32_e32 v2, v4, v2
	v_cmp_ne_u32_e32 vcc, v3, v2
	s_and_saveexec_b64 s[0:1], vcc
	s_xor_b64 s[0:1], exec, s[0:1]
	s_cbranch_execz .LBB0_191
	v_mov_b32_e32 v0, 0x3000
	global_load_dword v0, v0, s[8:9] offset:1024 sc1
	s_add_u32 s4, s8, 0x3400
	s_addc_u32 s5, s9, 0
	v_add_u32_e32 v1, 1, v1
	v_mul_lo_u32 v1, v1, v246
	s_waitcnt vmcnt(0)
	v_cmp_gt_u32_e32 vcc, v1, v0
	s_and_saveexec_b64 s[2:3], vcc
	s_cbranch_execz .LBB0_190
	s_mov_b32 s22, 1
	s_mov_b64 s[12:13], 0
	v_mov_b32_e32 v0, 0
	s_branch .LBB0_181

; __device__ __forceinline__ unsigned xb_ld(unsigned* p)              { return __hip_atomic_load(p, __ATOMIC_RELAXED, __HIP_MEMORY_SCOPE_AGENT); }
; #define XB_SPIN(cond, bar) do { unsigned _sp = 0; while (cond) { __builtin_amdgcn_s_sleep(1); \
;     if ((++_sp & 255u) == 0u) { if (xb_ld(&(bar)[XB_TMO])) break; if (_sp > XB_SPIN_CAP) { atomicAdd(&(bar)[XB_TMO], 1u); break; } } } } while (0)
; __device__ __forceinline__ void xcd_barrier(unsigned* bar, volatile LAS unsigned* st) {
;     ...
;       XB_SPIN(xb_ld(&bar[XB_XGEN(x)]) == gen, bar);
.LBB0_183:
	global_load_dword v2, v0, s[4:5] sc1
	s_add_i32 s22, s22, 1
	s_mov_b64 s[18:19], -1
	s_waitcnt vmcnt(0)
	v_cmp_le_u32_e32 vcc, v1, v2
	s_orn2_b64 s[16:17], vcc, exec
	s_branch .LBB0_180

; __device__ __forceinline__ unsigned xb_ld(unsigned* p)              { return __hip_atomic_load(p, __ATOMIC_RELAXED, __HIP_MEMORY_SCOPE_AGENT); }
; __device__ __forceinline__ unsigned xb_add(unsigned* p, unsigned v) { return __hip_atomic_fetch_add(p, v, __ATOMIC_RELAXED, __HIP_MEMORY_SCOPE_AGENT); }
; #define XB_SPIN(cond, bar) do { unsigned _sp = 0; while (cond) { __builtin_amdgcn_s_sleep(1); \
;     if ((++_sp & 255u) == 0u) { if (xb_ld(&(bar)[XB_TMO])) break; if (_sp > XB_SPIN_CAP) { atomicAdd(&(bar)[XB_TMO], 1u); break; } } } } while (0)
; __device__ __forceinline__ void xcd_barrier(unsigned* bar, volatile LAS unsigned* st) {
;     ...
;       const unsigned og = xb_add(&bar[XB_TOP], 1u);
;       const unsigned tg = og / nx;
;       if (og + 1u == (tg + 1u) * nx) xb_add(&bar[XB_TOPGEN], 1u);
;       else XB_SPIN(xb_ld(&bar[XB_TOPGEN]) == tg, bar);
.LBB0_194:
	s_or_b64 exec, exec, s[2:3]
	v_cvt_f32_u32_e32 v3, v0
	s_waitcnt vmcnt(0)
	v_readfirstlane_b32 s0, v2
	s_add_u32 s2, s8, 0x3500
	s_addc_u32 s3, s9, 0
	s_add_u32 s98, s8, 0x3400
	s_addc_u32 s99, s9, 0
	v_rcp_iflag_f32_e32 v3, v3
	v_add_u32_e32 v1, s0, v1
	v_add_u32_e32 v4, 1, v1
	s_mov_b64 s[4:5], -1
	v_mul_f32_e32 v2, 0x4f7ffffe, v3
	v_cvt_u32_f32_e32 v2, v2
	v_sub_u32_e32 v3, 0, v0
	v_mul_lo_u32 v3, v3, v2
	v_mul_hi_u32 v3, v2, v3
	v_add_u32_e32 v2, v2, v3
	v_mul_hi_u32 v2, v1, v2
	v_mul_lo_u32 v3, v2, v0
	v_sub_u32_e32 v1, v1, v3
	v_add_u32_e32 v5, 1, v2
	v_cmp_ge_u32_e32 vcc, v1, v0
	v_sub_u32_e32 v3, v1, v0
	s_nop 0
	v_cndmask_b32_e32 v2, v2, v5, vcc
	v_cndmask_b32_e32 v1, v1, v3, vcc
	v_add_u32_e32 v3, 1, v2
	v_cmp_ge_u32_e32 vcc, v1, v0
	s_nop 1
	v_cndmask_b32_e32 v2, v2, v3, vcc
	v_mul_lo_u32 v1, v0, v2
	v_add_u32_e32 v0, v1, v0
	v_mov_b32_e32 v245, v0
	v_cmp_ne_u32_e32 vcc, v4, v0
	v_mov_b64_e32 v[0:1], s[2:3]
	s_and_saveexec_b64 s[0:1], vcc
	s_cbranch_execz .LBB0_206
	v_mov_b32_e32 v0, 0
	global_load_dword v1, v0, s[98:99] sc1
	s_mov_b64 s[14:15], 0
	s_waitcnt vmcnt(0)
	v_cmp_gt_u32_e32 vcc, v245, v1
	s_and_saveexec_b64 s[12:13], vcc
	s_cbranch_execz .LBB0_205
	s_add_u32 s4, s8, 0x200
	s_addc_u32 s5, s9, 0
	s_mov_b32 s22, 1
	s_mov_b64 s[8:9], 0
	s_branch .LBB0_198

; __device__ __forceinline__ unsigned xb_ld(unsigned* p)              { return __hip_atomic_load(p, __ATOMIC_RELAXED, __HIP_MEMORY_SCOPE_AGENT); }
; #define XB_SPIN(cond, bar) do { unsigned _sp = 0; while (cond) { __builtin_amdgcn_s_sleep(1); \
;     if ((++_sp & 255u) == 0u) { if (xb_ld(&(bar)[XB_TMO])) break; if (_sp > XB_SPIN_CAP) { atomicAdd(&(bar)[XB_TMO], 1u); break; } } } } while (0)
; __device__ __forceinline__ void xcd_barrier(unsigned* bar, volatile LAS unsigned* st) {
;     ...
;       else XB_SPIN(xb_ld(&bar[XB_TOPGEN]) == tg, bar);
.LBB0_200:
	global_load_dword v1, v0, s[98:99] sc1
	s_add_i32 s22, s22, 1
	s_mov_b64 s[16:17], -1
	s_waitcnt vmcnt(0)
	v_cmp_le_u32_e32 vcc, v245, v1
	s_orn2_b64 s[20:21], vcc, exec
	s_branch .LBB0_197

; __device__ __forceinline__ unsigned xb_ld(unsigned* p)              { return __hip_atomic_load(p, __ATOMIC_RELAXED, __HIP_MEMORY_SCOPE_AGENT); }
; __device__ __forceinline__ unsigned xb_add(unsigned* p, unsigned v) { return __hip_atomic_fetch_add(p, v, __ATOMIC_RELAXED, __HIP_MEMORY_SCOPE_AGENT); }
; #define XB_SPIN(cond, bar) do { unsigned _sp = 0; while (cond) { __builtin_amdgcn_s_sleep(1); \
;     if ((++_sp & 255u) == 0u) { if (xb_ld(&(bar)[XB_TMO])) break; if (_sp > XB_SPIN_CAP) { atomicAdd(&(bar)[XB_TMO], 1u); break; } } } } while (0)
; __device__ __forceinline__ void xcd_barrier(unsigned* bar, volatile LAS unsigned* st) {
;     ...
;     const unsigned old = xb_add(&bar[XB_XSUB(x)], 1u);
;     const unsigned gen = old / nloc;
;     if (old + 1u == (gen + 1u) * nloc) {
;       __builtin_amdgcn_fence(__ATOMIC_RELEASE, "agent");
;       asm volatile("s_waitcnt vmcnt(0)" ::: "memory");
;       const unsigned og = xb_add(&bar[XB_TOP], 1u);
;       const unsigned tg = og / nx;
;       if (og + 1u == (tg + 1u) * nx) xb_add(&bar[XB_TOPGEN], 1u);
;       else XB_SPIN(xb_ld(&bar[XB_TOPGEN]) == tg, bar);
;       __builtin_amdgcn_fence(__ATOMIC_ACQUIRE, "agent");
;       xb_add(&bar[XB_XGEN(x)], 1u);
;       asm volatile("s_waitcnt vmcnt(0)" ::: "memory");
;     } else {
;       XB_SPIN(xb_ld(&bar[XB_XGEN(x)]) == gen, bar);
.LBB0_243:
	v_mov_b32_e32 v246, v0
	s_mov_b64 s[0:1], exec
	s_lshl_b32 s2, s18, 8
	v_mbcnt_lo_u32_b32 v1, s0, 0
	s_add_u32 s8, s10, s2
	v_mbcnt_hi_u32_b32 v1, s1, v1
	s_addc_u32 s9, s11, 0
	v_cmp_eq_u32_e32 vcc, 0, v1
	s_and_saveexec_b64 s[2:3], vcc
	s_cbranch_execz .LBB0_245
	s_bcnt1_i32_b64 s0, s[0:1]
	v_mov_b32_e32 v3, 0x1000
	v_mov_b32_e32 v4, s0
	global_atomic_add v3, v3, v4, s[8:9] offset:1024 sc0
.LBB0_245:
	s_or_b64 exec, exec, s[2:3]
	v_cvt_f32_u32_e32 v4, v2
	s_waitcnt vmcnt(0)
	v_readfirstlane_b32 s0, v3
	v_sub_u32_e32 v3, 0, v2
	v_rcp_iflag_f32_e32 v4, v4
	v_add_u32_e32 v5, s0, v1
	v_mul_f32_e32 v4, 0x4f7ffffe, v4
	v_cvt_u32_f32_e32 v4, v4
	v_mul_lo_u32 v1, v3, v4
	v_mul_hi_u32 v1, v4, v1
	v_add_u32_e32 v1, v4, v1
	v_mul_hi_u32 v1, v5, v1
	v_mul_lo_u32 v3, v1, v2
	v_sub_u32_e32 v3, v5, v3
	v_add_u32_e32 v4, 1, v1
	v_cmp_ge_u32_e32 vcc, v3, v2
	s_nop 1
	v_cndmask_b32_e32 v1, v1, v4, vcc
	v_sub_u32_e32 v4, v3, v2
	v_cndmask_b32_e32 v3, v3, v4, vcc
	v_add_u32_e32 v4, 1, v1
	v_cmp_ge_u32_e32 vcc, v3, v2
	v_add_u32_e32 v3, 1, v5
	s_nop 0
	v_cndmask_b32_e32 v1, v1, v4, vcc
	v_mul_lo_u32 v4, v2, v1
	v_add_u32_e32 v2, v4, v2
	v_cmp_ne_u32_e32 vcc, v3, v2
	s_and_saveexec_b64 s[0:1], vcc
	s_xor_b64 s[0:1], exec, s[0:1]
	s_cbranch_execz .LBB0_259
	v_mov_b32_e32 v0, 0x3000
	global_load_dword v0, v0, s[10:11] offset:1024 sc1
	s_add_u32 s4, s10, 0x3400
	s_addc_u32 s5, s11, 0
	v_add_u32_e32 v1, 1, v1
	v_mul_lo_u32 v1, v1, v246
	s_waitcnt vmcnt(0)
	v_cmp_gt_u32_e32 vcc, v1, v0
	s_and_saveexec_b64 s[2:3], vcc
	s_cbranch_execz .LBB0_258
	s_mov_b32 s22, 1
	s_mov_b64 s[12:13], 0
	v_mov_b32_e32 v0, 0
	s_branch .LBB0_249

; __device__ __forceinline__ unsigned xb_ld(unsigned* p)              { return __hip_atomic_load(p, __ATOMIC_RELAXED, __HIP_MEMORY_SCOPE_AGENT); }
; __device__ __forceinline__ unsigned xb_add(unsigned* p, unsigned v) { return __hip_atomic_fetch_add(p, v, __ATOMIC_RELAXED, __HIP_MEMORY_SCOPE_AGENT); }
; #define XB_SPIN(cond, bar) do { unsigned _sp = 0; while (cond) { __builtin_amdgcn_s_sleep(1); \
;     if ((++_sp & 255u) == 0u) { if (xb_ld(&(bar)[XB_TMO])) break; if (_sp > XB_SPIN_CAP) { atomicAdd(&(bar)[XB_TMO], 1u); break; } } } } while (0)
; __device__ __forceinline__ void xcd_barrier(unsigned* bar, volatile LAS unsigned* st) {
;     ...
;       const unsigned og = xb_add(&bar[XB_TOP], 1u);
;       const unsigned tg = og / nx;
;       if (og + 1u == (tg + 1u) * nx) xb_add(&bar[XB_TOPGEN], 1u);
;       else XB_SPIN(xb_ld(&bar[XB_TOPGEN]) == tg, bar);
.LBB0_262:
	s_or_b64 exec, exec, s[2:3]
	v_cvt_f32_u32_e32 v3, v0
	s_waitcnt vmcnt(0)
	v_readfirstlane_b32 s0, v2
	s_add_u32 s2, s10, 0x3500
	s_addc_u32 s3, s11, 0
	s_add_u32 s98, s10, 0x3400
	s_addc_u32 s99, s11, 0
	v_rcp_iflag_f32_e32 v3, v3
	v_add_u32_e32 v1, s0, v1
	v_add_u32_e32 v4, 1, v1
	s_mov_b64 s[4:5], -1
	v_mul_f32_e32 v2, 0x4f7ffffe, v3
	v_cvt_u32_f32_e32 v2, v2
	v_sub_u32_e32 v3, 0, v0
	v_mul_lo_u32 v3, v3, v2
	v_mul_hi_u32 v3, v2, v3
	v_add_u32_e32 v2, v2, v3
	v_mul_hi_u32 v2, v1, v2
	v_mul_lo_u32 v3, v2, v0
	v_sub_u32_e32 v1, v1, v3
	v_add_u32_e32 v5, 1, v2
	v_cmp_ge_u32_e32 vcc, v1, v0
	v_sub_u32_e32 v3, v1, v0
	s_nop 0
	v_cndmask_b32_e32 v2, v2, v5, vcc
	v_cndmask_b32_e32 v1, v1, v3, vcc
	v_add_u32_e32 v3, 1, v2
	v_cmp_ge_u32_e32 vcc, v1, v0
	s_nop 1
	v_cndmask_b32_e32 v2, v2, v3, vcc
	v_mul_lo_u32 v1, v0, v2
	v_add_u32_e32 v0, v1, v0
	v_mov_b32_e32 v245, v0
	v_cmp_ne_u32_e32 vcc, v4, v0
	v_mov_b64_e32 v[0:1], s[2:3]
	s_and_saveexec_b64 s[0:1], vcc
	s_cbranch_execz .LBB0_274
	v_mov_b32_e32 v0, 0
	global_load_dword v1, v0, s[98:99] sc1
	s_mov_b64 s[14:15], 0
	s_waitcnt vmcnt(0)
	v_cmp_gt_u32_e32 vcc, v245, v1
	s_and_saveexec_b64 s[12:13], vcc
	s_cbranch_execz .LBB0_273
	s_add_u32 s4, s10, 0x200
	s_addc_u32 s5, s11, 0
	s_mov_b32 s22, 1
	s_mov_b64 s[10:11], 0
	s_branch .LBB0_266

; __device__ __forceinline__ unsigned xb_add(unsigned* p, unsigned v) { return __hip_atomic_fetch_add(p, v, __ATOMIC_RELAXED, __HIP_MEMORY_SCOPE_AGENT); }
; __device__ __forceinline__ void xcd_barrier(unsigned* bar, volatile LAS unsigned* st) {
;     ...
;     const unsigned old = xb_add(&bar[XB_XSUB(x)], 1u);
;     const unsigned gen = old / nloc;
.LBB0_336:
	v_mov_b32_e32 v246, v0
	s_mov_b64 s[0:1], exec
	s_lshl_b32 s2, s18, 8
	v_mbcnt_lo_u32_b32 v1, s0, 0
	s_add_u32 s6, s10, s2
	v_mbcnt_hi_u32_b32 v1, s1, v1
	s_addc_u32 s7, s11, 0
	v_cmp_eq_u32_e32 vcc, 0, v1
	s_and_saveexec_b64 s[2:3], vcc
	s_cbranch_execz .LBB0_338
	s_bcnt1_i32_b64 s0, s[0:1]
	v_mov_b32_e32 v3, 0x1000
	v_mov_b32_e32 v4, s0
	global_atomic_add v3, v3, v4, s[6:7] offset:1024 sc0

; __device__ __forceinline__ unsigned xb_ld(unsigned* p)              { return __hip_atomic_load(p, __ATOMIC_RELAXED, __HIP_MEMORY_SCOPE_AGENT); }
; __device__ __forceinline__ unsigned xb_add(unsigned* p, unsigned v) { return __hip_atomic_fetch_add(p, v, __ATOMIC_RELAXED, __HIP_MEMORY_SCOPE_AGENT); }
; #define XB_SPIN(cond, bar) do { unsigned _sp = 0; while (cond) { __builtin_amdgcn_s_sleep(1); \
;     if ((++_sp & 255u) == 0u) { if (xb_ld(&(bar)[XB_TMO])) break; if (_sp > XB_SPIN_CAP) { atomicAdd(&(bar)[XB_TMO], 1u); break; } } } } while (0)
; __device__ __forceinline__ void xcd_barrier(unsigned* bar, volatile LAS unsigned* st) {
;     ...
;     const unsigned old = xb_add(&bar[XB_XSUB(x)], 1u);
;     const unsigned gen = old / nloc;
;     if (old + 1u == (gen + 1u) * nloc) {
;       __builtin_amdgcn_fence(__ATOMIC_RELEASE, "agent");
;       asm volatile("s_waitcnt vmcnt(0)" ::: "memory");
;       const unsigned og = xb_add(&bar[XB_TOP], 1u);
;       const unsigned tg = og / nx;
;       if (og + 1u == (tg + 1u) * nx) xb_add(&bar[XB_TOPGEN], 1u);
;       else XB_SPIN(xb_ld(&bar[XB_TOPGEN]) == tg, bar);
;       __builtin_amdgcn_fence(__ATOMIC_ACQUIRE, "agent");
;       xb_add(&bar[XB_XGEN(x)], 1u);
;       asm volatile("s_waitcnt vmcnt(0)" ::: "memory");
;     } else {
;       XB_SPIN(xb_ld(&bar[XB_XGEN(x)]) == gen, bar);
.LBB0_1287:
	s_or_b64 exec, exec, s[2:3]
	v_cvt_f32_u32_e32 v4, v2
	s_waitcnt vmcnt(0)
	v_readfirstlane_b32 s0, v3
	v_sub_u32_e32 v3, 0, v2
	v_rcp_iflag_f32_e32 v4, v4
	v_add_u32_e32 v5, s0, v1
	v_mul_f32_e32 v4, 0x4f7ffffe, v4
	v_cvt_u32_f32_e32 v4, v4
	v_mul_lo_u32 v1, v3, v4
	v_mul_hi_u32 v1, v4, v1
	v_add_u32_e32 v1, v4, v1
	v_mul_hi_u32 v1, v5, v1
	v_mul_lo_u32 v3, v1, v2
	v_sub_u32_e32 v3, v5, v3
	v_add_u32_e32 v4, 1, v1
	v_cmp_ge_u32_e32 vcc, v3, v2
	s_nop 1
	v_cndmask_b32_e32 v1, v1, v4, vcc
	v_sub_u32_e32 v4, v3, v2
	v_cndmask_b32_e32 v3, v3, v4, vcc
	v_add_u32_e32 v4, 1, v1
	v_cmp_ge_u32_e32 vcc, v3, v2
	v_add_u32_e32 v3, 1, v5
	s_nop 0
	v_cndmask_b32_e32 v1, v1, v4, vcc
	v_mul_lo_u32 v4, v2, v1
	v_add_u32_e32 v2, v4, v2
	v_cmp_ne_u32_e32 vcc, v3, v2
	s_and_saveexec_b64 s[0:1], vcc
	s_xor_b64 s[0:1], exec, s[0:1]
	s_cbranch_execz .LBB0_1301
	v_mov_b32_e32 v0, 0x3000
	global_load_dword v0, v0, s[8:9] offset:1024 sc1
	s_add_u32 s4, s8, 0x3400
	s_addc_u32 s5, s9, 0
	v_add_u32_e32 v1, 1, v1
	v_mul_lo_u32 v1, v1, v246
	s_waitcnt vmcnt(0)
	v_cmp_gt_u32_e32 vcc, v1, v0
	s_and_saveexec_b64 s[2:3], vcc
	s_cbranch_execz .LBB0_1300
	s_mov_b32 s23, 1
	s_mov_b64 s[12:13], 0
	v_mov_b32_e32 v0, 0
	s_branch .LBB0_1291

; __device__ __forceinline__ unsigned xb_ld(unsigned* p)              { return __hip_atomic_load(p, __ATOMIC_RELAXED, __HIP_MEMORY_SCOPE_AGENT); }
; #define XB_SPIN(cond, bar) do { unsigned _sp = 0; while (cond) { __builtin_amdgcn_s_sleep(1); \
;     if ((++_sp & 255u) == 0u) { if (xb_ld(&(bar)[XB_TMO])) break; if (_sp > XB_SPIN_CAP) { atomicAdd(&(bar)[XB_TMO], 1u); break; } } } } while (0)
; __device__ __forceinline__ void xcd_barrier(unsigned* bar, volatile LAS unsigned* st) {
;     ...
;       XB_SPIN(xb_ld(&bar[XB_XGEN(x)]) == gen, bar);
.LBB0_1293:
	global_load_dword v2, v0, s[4:5] sc1
	s_add_i32 s23, s23, 1
	s_mov_b64 s[18:19], -1
	s_waitcnt vmcnt(0)
	v_cmp_le_u32_e32 vcc, v1, v2
	s_orn2_b64 s[16:17], vcc, exec
	s_branch .LBB0_1290

; __device__ __forceinline__ unsigned xb_ld(unsigned* p)              { return __hip_atomic_load(p, __ATOMIC_RELAXED, __HIP_MEMORY_SCOPE_AGENT); }
; __device__ __forceinline__ unsigned xb_add(unsigned* p, unsigned v) { return __hip_atomic_fetch_add(p, v, __ATOMIC_RELAXED, __HIP_MEMORY_SCOPE_AGENT); }
; #define XB_SPIN(cond, bar) do { unsigned _sp = 0; while (cond) { __builtin_amdgcn_s_sleep(1); \
;     if ((++_sp & 255u) == 0u) { if (xb_ld(&(bar)[XB_TMO])) break; if (_sp > XB_SPIN_CAP) { atomicAdd(&(bar)[XB_TMO], 1u); break; } } } } while (0)
; __device__ __forceinline__ void xcd_barrier(unsigned* bar, volatile LAS unsigned* st) {
;     ...
;       const unsigned og = xb_add(&bar[XB_TOP], 1u);
;       const unsigned tg = og / nx;
;       if (og + 1u == (tg + 1u) * nx) xb_add(&bar[XB_TOPGEN], 1u);
;       else XB_SPIN(xb_ld(&bar[XB_TOPGEN]) == tg, bar);
.LBB0_1304:
	s_or_b64 exec, exec, s[2:3]
	v_cvt_f32_u32_e32 v3, v0
	s_waitcnt vmcnt(0)
	v_readfirstlane_b32 s0, v2
	s_add_u32 s2, s8, 0x3500
	s_addc_u32 s3, s9, 0
	s_add_u32 s98, s8, 0x3400
	s_addc_u32 s99, s9, 0
	v_rcp_iflag_f32_e32 v3, v3
	v_add_u32_e32 v1, s0, v1
	v_add_u32_e32 v4, 1, v1
	s_mov_b64 s[4:5], -1
	v_mul_f32_e32 v2, 0x4f7ffffe, v3
	v_cvt_u32_f32_e32 v2, v2
	v_sub_u32_e32 v3, 0, v0
	v_mul_lo_u32 v3, v3, v2
	v_mul_hi_u32 v3, v2, v3
	v_add_u32_e32 v2, v2, v3
	v_mul_hi_u32 v2, v1, v2
	v_mul_lo_u32 v3, v2, v0
	v_sub_u32_e32 v1, v1, v3
	v_add_u32_e32 v5, 1, v2
	v_cmp_ge_u32_e32 vcc, v1, v0
	v_sub_u32_e32 v3, v1, v0
	s_nop 0
	v_cndmask_b32_e32 v2, v2, v5, vcc
	v_cndmask_b32_e32 v1, v1, v3, vcc
	v_add_u32_e32 v3, 1, v2
	v_cmp_ge_u32_e32 vcc, v1, v0
	s_nop 1
	v_cndmask_b32_e32 v2, v2, v3, vcc
	v_mul_lo_u32 v1, v0, v2
	v_add_u32_e32 v0, v1, v0
	v_mov_b32_e32 v245, v0
	v_cmp_ne_u32_e32 vcc, v4, v0
	v_mov_b64_e32 v[0:1], s[2:3]
	s_and_saveexec_b64 s[0:1], vcc
	s_cbranch_execz .LBB0_1316
	v_mov_b32_e32 v0, 0
	global_load_dword v1, v0, s[98:99] sc1
	s_mov_b64 s[14:15], 0
	s_waitcnt vmcnt(0)
	v_cmp_gt_u32_e32 vcc, v245, v1
	s_and_saveexec_b64 s[12:13], vcc
	s_cbranch_execz .LBB0_1315
	s_add_u32 s4, s8, 0x200
	s_addc_u32 s5, s9, 0
	s_mov_b32 s23, 1
	s_mov_b64 s[8:9], 0
	s_branch .LBB0_1308

; __device__ __forceinline__ unsigned xb_ld(unsigned* p)              { return __hip_atomic_load(p, __ATOMIC_RELAXED, __HIP_MEMORY_SCOPE_AGENT); }
; #define XB_SPIN(cond, bar) do { unsigned _sp = 0; while (cond) { __builtin_amdgcn_s_sleep(1); \
;     if ((++_sp & 255u) == 0u) { if (xb_ld(&(bar)[XB_TMO])) break; if (_sp > XB_SPIN_CAP) { atomicAdd(&(bar)[XB_TMO], 1u); break; } } } } while (0)
; __device__ __forceinline__ void xcd_barrier(unsigned* bar, volatile LAS unsigned* st) {
;     ...
;       else XB_SPIN(xb_ld(&bar[XB_TOPGEN]) == tg, bar);
.LBB0_1310:
	global_load_dword v1, v0, s[98:99] sc1
	s_add_i32 s23, s23, 1
	s_mov_b64 s[16:17], -1
	s_waitcnt vmcnt(0)
	v_cmp_le_u32_e32 vcc, v245, v1
	s_orn2_b64 s[20:21], vcc, exec
	s_branch .LBB0_1307

; __device__ __forceinline__ unsigned xb_ld(unsigned* p)              { return __hip_atomic_load(p, __ATOMIC_RELAXED, __HIP_MEMORY_SCOPE_AGENT); }
; __device__ __forceinline__ unsigned xb_add(unsigned* p, unsigned v) { return __hip_atomic_fetch_add(p, v, __ATOMIC_RELAXED, __HIP_MEMORY_SCOPE_AGENT); }
; #define XB_SPIN(cond, bar) do { unsigned _sp = 0; while (cond) { __builtin_amdgcn_s_sleep(1); \
;     if ((++_sp & 255u) == 0u) { if (xb_ld(&(bar)[XB_TMO])) break; if (_sp > XB_SPIN_CAP) { atomicAdd(&(bar)[XB_TMO], 1u); break; } } } } while (0)
; __device__ __forceinline__ void xcd_barrier(unsigned* bar, volatile LAS unsigned* st) {
;     ...
;     const unsigned old = xb_add(&bar[XB_XSUB(x)], 1u);
;     const unsigned gen = old / nloc;
;     if (old + 1u == (gen + 1u) * nloc) {
;       __builtin_amdgcn_fence(__ATOMIC_RELEASE, "agent");
;       asm volatile("s_waitcnt vmcnt(0)" ::: "memory");
;       const unsigned og = xb_add(&bar[XB_TOP], 1u);
;       const unsigned tg = og / nx;
;       if (og + 1u == (tg + 1u) * nx) xb_add(&bar[XB_TOPGEN], 1u);
;       else XB_SPIN(xb_ld(&bar[XB_TOPGEN]) == tg, bar);
;       __builtin_amdgcn_fence(__ATOMIC_ACQUIRE, "agent");
;       xb_add(&bar[XB_XGEN(x)], 1u);
;       asm volatile("s_waitcnt vmcnt(0)" ::: "memory");
;     } else {
;       XB_SPIN(xb_ld(&bar[XB_XGEN(x)]) == gen, bar);
.LBB0_2716:
	v_mov_b32_e32 v246, v0
	s_mov_b64 s[0:1], exec
	s_lshl_b32 s2, s18, 8
	v_mbcnt_lo_u32_b32 v1, s0, 0
	s_add_u32 s8, s4, s2
	v_mbcnt_hi_u32_b32 v1, s1, v1
	s_addc_u32 s9, s5, 0
	v_cmp_eq_u32_e32 vcc, 0, v1
	s_and_saveexec_b64 s[2:3], vcc
	s_cbranch_execz .LBB0_2718
	s_bcnt1_i32_b64 s0, s[0:1]
	v_mov_b32_e32 v3, 0x1000
	v_mov_b32_e32 v4, s0
	global_atomic_add v3, v3, v4, s[8:9] offset:1024 sc0
.LBB0_2718:
	s_or_b64 exec, exec, s[2:3]
	v_cvt_f32_u32_e32 v4, v2
	s_waitcnt vmcnt(0)
	v_readfirstlane_b32 s0, v3
	v_sub_u32_e32 v3, 0, v2
	v_rcp_iflag_f32_e32 v4, v4
	v_add_u32_e32 v5, s0, v1
	v_mul_f32_e32 v4, 0x4f7ffffe, v4
	v_cvt_u32_f32_e32 v4, v4
	v_mul_lo_u32 v1, v3, v4
	v_mul_hi_u32 v1, v4, v1
	v_add_u32_e32 v1, v4, v1
	v_mul_hi_u32 v1, v5, v1
	v_mul_lo_u32 v3, v1, v2
	v_sub_u32_e32 v3, v5, v3
	v_add_u32_e32 v4, 1, v1
	v_cmp_ge_u32_e32 vcc, v3, v2
	s_nop 1
	v_cndmask_b32_e32 v1, v1, v4, vcc
	v_sub_u32_e32 v4, v3, v2
	v_cndmask_b32_e32 v3, v3, v4, vcc
	v_add_u32_e32 v4, 1, v1
	v_cmp_ge_u32_e32 vcc, v3, v2
	v_add_u32_e32 v3, 1, v5
	s_nop 0
	v_cndmask_b32_e32 v1, v1, v4, vcc
	v_mul_lo_u32 v4, v2, v1
	v_add_u32_e32 v2, v4, v2
	v_cmp_ne_u32_e32 vcc, v3, v2
	s_and_saveexec_b64 s[0:1], vcc
	s_xor_b64 s[0:1], exec, s[0:1]
	s_cbranch_execz .LBB0_2732
	v_mov_b32_e32 v0, 0x3000
	global_load_dword v0, v0, s[4:5] offset:1024 sc1
	s_add_u32 s10, s4, 0x3400
	s_addc_u32 s11, s5, 0
	v_add_u32_e32 v1, 1, v1
	v_mul_lo_u32 v1, v1, v246
	s_waitcnt vmcnt(0)
	v_cmp_gt_u32_e32 vcc, v1, v0
	s_and_saveexec_b64 s[2:3], vcc
	s_cbranch_execz .LBB0_2731
	s_mov_b32 s22, 1
	s_mov_b64 s[12:13], 0
	v_mov_b32_e32 v0, 0
	s_branch .LBB0_2722

; __device__ __forceinline__ unsigned xb_ld(unsigned* p)              { return __hip_atomic_load(p, __ATOMIC_RELAXED, __HIP_MEMORY_SCOPE_AGENT); }
; #define XB_SPIN(cond, bar) do { unsigned _sp = 0; while (cond) { __builtin_amdgcn_s_sleep(1); \
;     if ((++_sp & 255u) == 0u) { if (xb_ld(&(bar)[XB_TMO])) break; if (_sp > XB_SPIN_CAP) { atomicAdd(&(bar)[XB_TMO], 1u); break; } } } } while (0)
; __device__ __forceinline__ void xcd_barrier(unsigned* bar, volatile LAS unsigned* st) {
;     ...
;       XB_SPIN(xb_ld(&bar[XB_XGEN(x)]) == gen, bar);
.LBB0_2724:
	global_load_dword v2, v0, s[10:11] sc1
	s_add_i32 s22, s22, 1
	s_mov_b64 s[18:19], -1
	s_waitcnt vmcnt(0)
	v_cmp_le_u32_e32 vcc, v1, v2
	s_orn2_b64 s[16:17], vcc, exec
	s_branch .LBB0_2721

; __device__ __forceinline__ unsigned xb_ld(unsigned* p)              { return __hip_atomic_load(p, __ATOMIC_RELAXED, __HIP_MEMORY_SCOPE_AGENT); }
; __device__ __forceinline__ unsigned xb_add(unsigned* p, unsigned v) { return __hip_atomic_fetch_add(p, v, __ATOMIC_RELAXED, __HIP_MEMORY_SCOPE_AGENT); }
; #define XB_SPIN(cond, bar) do { unsigned _sp = 0; while (cond) { __builtin_amdgcn_s_sleep(1); \
;     if ((++_sp & 255u) == 0u) { if (xb_ld(&(bar)[XB_TMO])) break; if (_sp > XB_SPIN_CAP) { atomicAdd(&(bar)[XB_TMO], 1u); break; } } } } while (0)
; __device__ __forceinline__ void xcd_barrier(unsigned* bar, volatile LAS unsigned* st) {
;     ...
;       const unsigned og = xb_add(&bar[XB_TOP], 1u);
;       const unsigned tg = og / nx;
;       if (og + 1u == (tg + 1u) * nx) xb_add(&bar[XB_TOPGEN], 1u);
;       else XB_SPIN(xb_ld(&bar[XB_TOPGEN]) == tg, bar);
.LBB0_2735:
	s_or_b64 exec, exec, s[2:3]
	v_cvt_f32_u32_e32 v3, v0
	s_waitcnt vmcnt(0)
	v_readfirstlane_b32 s0, v2
	s_add_u32 s2, s4, 0x3500
	s_addc_u32 s3, s5, 0
	s_add_u32 s98, s4, 0x3400
	s_addc_u32 s99, s5, 0
	v_rcp_iflag_f32_e32 v3, v3
	v_add_u32_e32 v1, s0, v1
	v_add_u32_e32 v4, 1, v1
	s_mov_b64 s[10:11], -1
	v_mul_f32_e32 v2, 0x4f7ffffe, v3
	v_cvt_u32_f32_e32 v2, v2
	v_sub_u32_e32 v3, 0, v0
	v_mul_lo_u32 v3, v3, v2
	v_mul_hi_u32 v3, v2, v3
	v_add_u32_e32 v2, v2, v3
	v_mul_hi_u32 v2, v1, v2
	v_mul_lo_u32 v3, v2, v0
	v_sub_u32_e32 v1, v1, v3
	v_add_u32_e32 v5, 1, v2
	v_cmp_ge_u32_e32 vcc, v1, v0
	v_sub_u32_e32 v3, v1, v0
	s_nop 0
	v_cndmask_b32_e32 v2, v2, v5, vcc
	v_cndmask_b32_e32 v1, v1, v3, vcc
	v_add_u32_e32 v3, 1, v2
	v_cmp_ge_u32_e32 vcc, v1, v0
	s_nop 1
	v_cndmask_b32_e32 v2, v2, v3, vcc
	v_mul_lo_u32 v1, v0, v2
	v_add_u32_e32 v0, v1, v0
	v_mov_b32_e32 v245, v0
	v_cmp_ne_u32_e32 vcc, v4, v0
	v_mov_b64_e32 v[0:1], s[2:3]
	s_and_saveexec_b64 s[0:1], vcc
	s_cbranch_execz .LBB0_2747
	v_mov_b32_e32 v0, 0
	global_load_dword v1, v0, s[98:99] sc1
	s_mov_b64 s[14:15], 0
	s_waitcnt vmcnt(0)
	v_cmp_gt_u32_e32 vcc, v245, v1
	s_and_saveexec_b64 s[12:13], vcc
	s_cbranch_execz .LBB0_2746
	s_add_u32 s10, s4, 0x200
	s_addc_u32 s11, s5, 0
	s_mov_b32 s22, 1
	s_mov_b64 s[4:5], 0
	s_branch .LBB0_2739

; __global__ void __launch_bounds__(NTHR, 2) mega(Params p, int ph0, int ph1) {
	.amdhsa_kernel _Z4mega6Paramsii
		.amdhsa_group_segment_fixed_size 0
		.amdhsa_private_segment_fixed_size 0
		.amdhsa_kernarg_size 616
		.amdhsa_user_sgpr_count 2
		.amdhsa_user_sgpr_dispatch_ptr 0
		.amdhsa_user_sgpr_queue_ptr 0
		.amdhsa_user_sgpr_kernarg_segment_ptr 1
		.amdhsa_user_sgpr_dispatch_id 0
		.amdhsa_user_sgpr_kernarg_preload_length 0
		.amdhsa_user_sgpr_kernarg_preload_offset 0
		.amdhsa_user_sgpr_private_segment_size 0
		.amdhsa_uses_dynamic_stack 0
		.amdhsa_enable_private_segment 0
		.amdhsa_system_sgpr_workgroup_id_x 1
		.amdhsa_system_sgpr_workgroup_id_y 0
		.amdhsa_system_sgpr_workgroup_id_z 0
		.amdhsa_system_sgpr_workgroup_info 0
		.amdhsa_system_vgpr_workitem_id 2
		.amdhsa_next_free_vgpr 248
		.amdhsa_next_free_sgpr 102
		.amdhsa_accum_offset 248
		.amdhsa_reserve_vcc 1
		.amdhsa_float_round_mode_32 0
		.amdhsa_float_round_mode_16_64 0
		.amdhsa_float_denorm_mode_32 3
		.amdhsa_float_denorm_mode_16_64 3
		.amdhsa_dx10_clamp 1
		.amdhsa_ieee_mode 1
		.amdhsa_fp16_overflow 0
		.amdhsa_tg_split 0
		.amdhsa_exception_fp_ieee_invalid_op 0
		.amdhsa_exception_fp_denorm_src 0
		.amdhsa_exception_fp_ieee_div_zero 0
		.amdhsa_exception_fp_ieee_overflow 0
		.amdhsa_exception_fp_ieee_underflow 0
		.amdhsa_exception_fp_ieee_inexact 0
		.amdhsa_exception_int_div_zero 0
	.end_amdhsa_kernel

; __global__ void __launch_bounds__(NTHR, 2) mega(Params p, int ph0, int ph1) {
amdhsa.kernels:
  - .agpr_count:     0
    .args:
      - .offset:         0
        .size:           352
        .value_kind:     by_value
      - .offset:         352
        .size:           4
        .value_kind:     by_value
      - .offset:         356
        .size:           4
        .value_kind:     by_value
      - .offset:         360
        .size:           4
        .value_kind:     hidden_block_count_x
      - .offset:         364
        .size:           4
        .value_kind:     hidden_block_count_y
      - .offset:         368
        .size:           4
        .value_kind:     hidden_block_count_z
      - .offset:         372
        .size:           2
        .value_kind:     hidden_group_size_x
      - .offset:         374
        .size:           2
        .value_kind:     hidden_group_size_y
      - .offset:         376
        .size:           2
        .value_kind:     hidden_group_size_z
      - .offset:         378
        .size:           2
        .value_kind:     hidden_remainder_x
      - .offset:         380
        .size:           2
        .value_kind:     hidden_remainder_y
      - .offset:         382
        .size:           2
        .value_kind:     hidden_remainder_z
      - .offset:         400
        .size:           8
        .value_kind:     hidden_global_offset_x
      - .offset:         408
        .size:           8
        .value_kind:     hidden_global_offset_y
      - .offset:         416
        .size:           8
        .value_kind:     hidden_global_offset_z
      - .offset:         424
        .size:           2
        .value_kind:     hidden_grid_dims
      - .offset:         448
        .size:           8
        .value_kind:     hidden_multigrid_sync_arg
      - .offset:         480
        .size:           4
        .value_kind:     hidden_dynamic_lds_size
    .group_segment_fixed_size: 0
    .kernarg_segment_align: 8
    .kernarg_segment_size: 616
    .language:       OpenCL C
    .language_version:
      - 2
      - 0
    .max_flat_workgroup_size: 512
    .name:           _Z4mega6Paramsii
    .private_segment_fixed_size: 0
    .sgpr_count:     108
    .sgpr_spill_count: 41
    .symbol:         _Z4mega6Paramsii.kd
    .uniform_work_group_size: 1
    .uses_dynamic_stack: false
    .vgpr_count:     248
    .vgpr_spill_count: 0
    .wavefront_size: 64
